# static s_setprio 1 for waves 0-3 only outside the GEMM phases
# speedup vs baseline: 1.0067x; 1.0067x over previous
; #define LAS __attribute__((address_space(3)))
; __device__ __forceinline__ void p0_late_weights(Frame& F, int gw, int NGW) {
;     LAS float* scr = (LAS float*)(F.lds + F.wave * 16384);
;     constexpr int I_OUT = (DM / 64) * (DM / 64), I_UP = (DM / 64) * (2 * DFF / 64), I_DN = (DFF / 64) * (DM / 64);
;     for (int it = gw; it < I_UP + I_DN + I_OUT; it += NGW) {
;         int r = it;
;         if (r < I_UP) { const int nblk = 2 * DFF / 64, kb = r / nblk, nb = r % nblk; const int n0 = 64 * nb, half = n0 / DFF, j = n0 % DFF;
;             p0_transpose_item(F.in[25], 2 * DFF, 64 * kb, n0, F.in[24], WSP(bf16_t, WS_BT3), DM, (j / 128) * 256 + half * 128 + (j % 128), scr, F.lane, (unsigned*)(F.ws + WS_CTL) + CW_CMAX3); continue; } r -= I_UP;
; __global__ void __launch_bounds__(512, 2) mk_fwd(Args args) {
;     ...
;     if (IN(1)) {
;         const bool roles = (F.G == 256);
;         const int x = (int)blockIdx.x & 7, j = (int)blockIdx.x >> 3; const bool is_gemm = !roles || j < G1_PER + (x < G1_HI ? 1 : 0);
;         if (!is_gemm) { const int sidx = (j == G1_PER) ? x - G1_HI : (8 - G1_HI) + (j - G1_PER - 1) * 8 + x; p0_late_weights(F, sidx * 8 + F.wave, NSTREAM * 8); }
.LBB0_148:
	s_setprio 0
	v_writelane_b32 v254, s72, 41
	s_cmp_lt_i32 s90, 2
	s_cselect_b64 s[2:3], -1, 0
	v_writelane_b32 v254, s73, 42
	v_writelane_b32 v254, s74, 43
	v_writelane_b32 v254, s75, 44
	v_writelane_b32 v254, s76, 45
	v_writelane_b32 v254, s77, 46
	v_writelane_b32 v254, s78, 47
	v_writelane_b32 v254, s79, 48
	v_writelane_b32 v254, s80, 49
	v_writelane_b32 v254, s81, 50
	v_writelane_b32 v254, s82, 51
	v_writelane_b32 v254, s83, 52
	v_writelane_b32 v254, s84, 53
	v_writelane_b32 v254, s85, 54
	v_writelane_b32 v254, s86, 55
	s_and_b64 s[28:29], s[2:3], s[0:1]
	v_writelane_b32 v254, s87, 56
	s_mov_b32 s0, s96
	v_writelane_b32 v254, s0, 57
	s_andn2_b64 vcc, exec, s[28:29]
	s_nop 0
	v_writelane_b32 v254, s1, 58
	s_cbranch_vccnz .LBB0_1796
	s_cmpk_lg_i32 s96, 0x100
	s_cselect_b64 s[0:1], -1, 0
	s_and_b32 s15, s92, 7
	s_ashr_i32 s14, s92, 3
	s_cmp_lt_u32 s15, 2
	s_cselect_b32 s2, 27, 26
	s_cmp_lt_i32 s14, s2
	s_cselect_b64 s[2:3], -1, 0
	s_or_b64 s[4:5], s[0:1], s[2:3]
	s_mov_b64 s[2:3], -1
	s_and_b64 vcc, exec, s[4:5]
	s_cbranch_vccnz .LBB0_182
	s_and_b32 s2, s92, 0x1ffffff8
	s_addk_i32 s2, 0xff2e
	s_cmp_lg_u32 s14, 26
	s_cselect_b32 s2, s2, -2
	s_add_i32 s2, s2, s15
	s_lshl_b32 s2, s2, 3
	v_readlane_b32 s3, v254, 39
	s_add_i32 s16, s3, s2
	s_cmp_gt_i32 s16, 0x9fff
	s_cbranch_scc1 .LBB0_181
	v_readlane_b32 s2, v254, 39
	s_lshl_b32 s2, s2, 14
	v_lshlrev_b32_e32 v2, 2, v0
	s_add_i32 s2, s2, 0
	v_lshrrev_b32_e32 v1, 4, v238
	v_and_b32_e32 v3, 60, v2
	v_lshlrev_b32_e32 v66, 2, v3
	v_lshl_add_u32 v3, v1, 8, s2
	v_bitop3_b32 v4, v2, 8, 60 bitop3:0x6c
	v_lshl_add_u32 v84, v4, 2, v3
	v_bitop3_b32 v4, v2, 16, 60 bitop3:0x6c
	v_lshl_add_u32 v85, v4, 2, v3
	v_bitop3_b32 v4, v2, 24, 60 bitop3:0x6c
	v_lshl_add_u32 v86, v4, 2, v3
	v_bitop3_b32 v4, v2, 32, 60 bitop3:0x6c
	v_lshl_add_u32 v87, v4, 2, v3
	v_bitop3_b32 v4, v2, 40, 60 bitop3:0x6c
	v_lshl_add_u32 v88, v4, 2, v3
	v_bitop3_b32 v4, v2, 48, 60 bitop3:0x6c
	v_lshl_add_u32 v89, v4, 2, v3
	v_bitop3_b32 v2, v2, 56, 60 bitop3:0x6c
	v_and_b32_e32 v4, 7, v0
	s_waitcnt lgkmcnt(0)
	v_lshrrev_b32_e32 v6, 1, v238
	v_add_u32_e32 v71, v3, v66
	v_lshl_add_u32 v90, v2, 2, v3
	v_lshrrev_b32_e32 v70, 3, v238
	v_lshlrev_b32_e32 v2, 11, v4
	v_and_b32_e32 v3, 12, v6
	v_readlane_b32 s52, v254, 18
	v_lshlrev_b32_e32 v5, 3, v4
	v_add3_u32 v7, s2, v2, v3
	v_and_b32_e32 v6, 16, v6
	v_lshlrev_b32_e32 v8, 5, v4
	v_or_b32_e32 v92, 8, v70
	v_readlane_b32 s64, v254, 30
	v_mov_b32_e32 v67, 0
	v_add3_u32 v91, v7, v6, v8
	v_bitop3_b32 v6, v92, v5, 12 bitop3:0x6c
	v_or_b32_e32 v94, 16, v70
	v_readlane_b32 s65, v254, 31
	s_add_u32 s17, s64, 0xffffe000
	v_lshlrev_b32_e32 v2, 4, v4
	v_mov_b32_e32 v3, v67
	v_lshl_add_u32 v93, v6, 2, v7
	v_bitop3_b32 v6, v94, v5, 20 bitop3:0x6c
	v_or_b32_e32 v96, 24, v70
	s_addc_u32 s18, s65, -1
	v_lshl_add_u64 v[2:3], s[86:87], 0, v[2:3]
	s_mov_b64 s[4:5], 0x4b00000
	v_lshl_add_u32 v95, v6, 2, v7
	v_bitop3_b32 v6, v96, v5, 28 bitop3:0x6c
	v_or_b32_e32 v98, 32, v70
	v_lshl_add_u64 v[72:73], v[2:3], 0, s[4:5]
	v_lshl_add_u32 v97, v6, 2, v7
	v_bitop3_b32 v6, v98, v5, 36 bitop3:0x6c
	v_or_b32_e32 v100, 40, v70
	s_mov_b64 s[4:5], 0x12b00000
	s_add_u32 s19, s86, 0x29aa8
	v_lshl_add_u32 v99, v6, 2, v7
	v_bitop3_b32 v6, v100, v5, 44 bitop3:0x6c
	v_or_b32_e32 v102, 48, v70
	v_or_b32_e32 v104, 56, v70
	v_lshl_add_u64 v[76:77], v[2:3], 0, s[4:5]
	s_addc_u32 s20, s87, 0
	s_mov_b64 s[4:5], 0x6b00000
	v_readlane_b32 s66, v254, 32
	v_readlane_b32 s67, v254, 33
	v_lshl_add_u32 v101, v6, 2, v7
	v_bitop3_b32 v6, v102, v5, 52 bitop3:0x6c
	v_bitop3_b32 v5, v104, v5, 60 bitop3:0x6c
	s_cmp_lg_u64 s[72:73], 0
	v_lshl_add_u64 v[80:81], v[2:3], 0, s[4:5]
	v_mbcnt_lo_u32_b32 v2, -1, 0
	s_mov_b32 s3, 0
	v_lshl_add_u64 v[68:69], s[66:67], 0, v[66:67]
	v_lshl_add_u32 v103, v6, 2, v7
	v_lshl_add_u32 v105, v5, 2, v7
	v_lshl_add_u64 v[74:75], s[80:81], 0, v[66:67]
	v_lshl_add_u64 v[78:79], s[74:75], 0, v[66:67]
	s_cselect_b64 s[6:7], -1, 0
	v_cmp_eq_u32_e64 s[4:5], 0, v4
	s_lshl_b32 s21, s16, 6
	s_mov_b32 s24, 0x18000
	v_mbcnt_hi_u32_b32 v106, -1, v2
	v_readlane_b32 s53, v254, 19
	v_readlane_b32 s54, v254, 20
	v_readlane_b32 s55, v254, 21
	v_readlane_b32 s56, v254, 22
	v_readlane_b32 s57, v254, 23
	v_readlane_b32 s58, v254, 24
	v_readlane_b32 s59, v254, 25
	v_readlane_b32 s60, v254, 26
	v_readlane_b32 s61, v254, 27
	v_readlane_b32 s62, v254, 28
	v_readlane_b32 s63, v254, 29
	s_branch .LBB0_154

; #define LAS __attribute__((address_space(3)))
; #define SEAM(k) do { if (IN(k) && IN((k) + 1)) xcd_barrier(bar); } while (0)
; __device__ __forceinline__ void p4_scan(Frame& F) {
;     const unsigned* AB = WSP(unsigned, WS_AB); const bf16_t* G2 = WSP(bf16_t, WS_G2); bf16_t* CAT = WSP(bf16_t, WS_CAT); float* SSQ = WSP(float, WS_SSQRG);
;     LAS f32x2* carr = (LAS f32x2*)F.lds;
;     for (int u = blockIdx.x; u < NB * 64; u += F.G) {
; __global__ void __launch_bounds__(512, 2) mk_fwd(Args args) {
;     ...
;     if (IN(4)) { p4_scan(F); } SEAM(4);
.LBB0_2004:
	s_cmp_lt_u32 s98, 4
	s_cbranch_scc0 .Lprio_x2
	s_setprio 1
.Lprio_x2:
	s_cmp_lt_i32 s90, 5
	s_cselect_b64 s[2:3], -1, 0
	s_and_b64 s[22:23], s[2:3], s[0:1]
	s_andn2_b64 vcc, exec, s[22:23]
	s_cbranch_vccnz .LBB0_2040
	s_add_u32 s24, s86, 0x52db9000
	s_addc_u32 s25, s87, 0
	s_cmpk_lt_i32 s92, 0x100
	s_cbranch_scc1 .LBB0_2007
	v_mov_b32_e32 v1, 0
	s_cbranch_execz .LBB0_2008
	s_branch .LBB0_2026

; template <class Epi, class Geom, class Sched, bool ALIGN_EPI, bool I8 = false>
; __device__ __forceinline__ void gemm_phase(LAS unsigned char* lds, const Gemm g, const Sched& S, const Epi& E) {
;     const int tid = threadIdx.x, wid = __builtin_amdgcn_readfirstlane(tid >> 6), lane = tid & 63, wr = wid >> 2, wc = wid & 3, fr = lane & 15, fq = lane >> 4;
;     const int K = g.K, nt = K / BK;
;     unsigned voffA[2], voffB[2];
; #pragma unroll
;     for (int i = 0; i < 2; ++i) { int R, C; stage_rc(tid * 16 + i * 8192, R, C); const int Rb = Epi::PERM ? ((R & ~31) + perm32(R & 31)) : R;
;         voffA[i] = (unsigned)(R * g.lda + C) * 2u; voffB[i] = (unsigned)(Rb * g.ldb + C) * 2u; }
;     const size_t kstep = (size_t)(BK * 2);
;     const size_t hsA = (size_t)HALF * g.lda * 2, hsB = (size_t)HALF * g.ldb * 2;
;     const unsigned ldsw = (unsigned)wid * 1024u;
;     const int aoff = lds_byte(wr * 64 + fr, fq * 8), boff = lds_byte(wc * 32 + fr, fq * 8);
;     ...
;     Unit cur, nxt; int ui = 0;
;     if (!S.next(0, cur)) return;
;     f32x4 acc[2][2][4][2];
; #pragma unroll
;     for (int a = 0; a < 2; ++a)
; #pragma unroll
;         for (int b = 0; b < 2; ++b)
; #pragma unroll
;             for (int m = 0; m < 4; ++m)
; #pragma unroll
;                 for (int n = 0; n < 2; ++n) acc[a][b][m][n] = (f32x4){0.f, 0.f, 0.f, 0.f};
;     bf16x8 At[4][2], B0[2][2], B1[2][2];
;     const char* cA = (const char*)g.A + Geom::a_off(g, cur); const char* cB = (const char*)g.Bt + Geom::b_off(g, cur);
;     PG8_STAGE(PG8_SB(0, 0), cB, voffB); PG8_STAGE(PG8_SB(0, 1), cB + hsB, voffB); PG8_STAGE(PG8_SA(0, 0), cA, voffA); PG8_STAGE(PG8_SA(0, 1), cA + hsA, voffA);
;     if (wr == 1) PG8_BAR;
;     PG8_WAIT_V(2); PG8_BAR;
;     PG8_STAGE(PG8_SB(1, 0), cB + kstep, voffB); PG8_STAGE(PG8_SA(1, 0), cA + kstep, voffA); PG8_STAGE(PG8_SB(1, 1), cB + hsB + kstep, voffB);
; __global__ void __launch_bounds__(512, 2) mk_fwd(Args args) {
;     ...
;     if (IN(6)) { pg8::Gemm g{WSP(bf16_t, WS_CATQ), WSP(bf16_t, WS_BT2Q), M, DM, DM / 2, DM / 2, DM / 2}; pg8::StaticOrder S; S.init(M, DM, F.G, (int)blockIdx.x);
;         const bool split = (F.G == 256); if (split) S.limit = REM_FIRST;
;         EpiX1Q E{F.in[0], F.in[1], WSP(bf16_t, WS_X1), WSP(float, WS_SA2), WSP(float, WS_SW2)};
;         pg8::gemm_phase<EpiX1Q, pg8::GeomPlain, pg8::StaticOrder, true, true>(F.lds, g, S, E);
.LBB0_2221:
	s_setprio 0
	s_cmp_lt_i32 s90, 7
	s_cselect_b64 s[0:1], -1, 0
	s_and_b64 s[0:1], s[0:1], s[2:3]
	v_bfe_u32 v235, v0, 4, 2
	s_andn2_b64 vcc, exec, s[0:1]
	v_bfe_u32 v239, v0, 2, 4
	v_and_b32_e32 v241, 32, v0
	v_and_b32_e32 v236, 64, v0
	v_lshlrev_b32_e32 v237, 4, v235
	v_lshlrev_b32_e32 v240, 6, v0
	s_cbranch_vccnz .LBB0_2247
	s_add_u32 s33, s86, 0x2830f000
	s_addc_u32 s38, s87, 0
	s_add_u32 s39, s86, 0x59f0f000
	s_addc_u32 s40, s87, 0
	s_cmpk_eq_i32 s96, 0x100
	s_cselect_b64 s[2:3], -1, 0
	s_movk_i32 s6, 0x200
	s_and_b64 s[4:5], s[2:3], exec
	s_waitcnt vmcnt(0)
	v_bitop3_b32 v10, v234, v241, 48 bitop3:0x6c
	v_lshrrev_b32_e32 v2, 3, v0
	s_cselect_b32 s10, s6, 0x220
	s_add_u32 s6, s86, 0x5af0f000
	v_or_b32_e32 v1, v10, v236
	v_and_or_b32 v2, v2, 48, v239
	v_or_b32_e32 v11, 0x2000, v234
	s_addc_u32 s7, s87, 0
	v_lshl_or_b32 v146, v2, 12, v1
	v_lshrrev_b32_e32 v2, 7, v11
	s_movk_i32 s4, 0x70
	s_add_u32 s8, s86, 0x5af17800
	v_and_or_b32 v2, v2, s4, v239
	s_addc_u32 s9, s87, 0
	v_lshl_or_b32 v148, v2, 12, v1
	v_and_b32_e32 v1, 0x3c0, v240
	v_and_b32_e32 v2, 32, v233
	v_readfirstlane_b32 s5, v0
	s_cmp_ge_i32 s92, s10
	v_bitop3_b32 v1, v237, v2, v1 bitop3:0x36
	s_cbranch_scc1 .LBB0_2238
	s_ashr_i32 s42, s92, 31
	s_lshr_b32 s4, s42, 29
	s_add_i32 s4, s92, s4
	s_lshr_b32 s16, s5, 6
	s_ashr_i32 s11, s4, 3
	s_and_b32 s4, s4, -8
	s_lshr_b32 s18, s5, 8
	s_lshl_b32 s41, s16, 10
	s_sub_i32 s4, s92, s4
	s_cmp_lt_i32 s4, 0
	s_movk_i32 s43, 0x45
	s_cselect_b32 s12, s43, 0x44
	s_mul_i32 s4, s4, s12
	s_add_i32 s4, s4, s11
	s_ashr_i32 s11, s4, 31
	s_lshr_b32 s11, s11, 25
	s_add_i32 s11, s4, s11
	s_ashr_i32 s12, s11, 7
	s_lshl_b32 s14, s12, 3
	s_sub_i32 s12, 34, s14
	s_min_u32 s15, s12, 8
	s_and_b32 s11, s11, 0xffffff80
	s_sub_i32 s11, s4, s11
	v_cvt_f32_ubyte0_e32 v3, s15
	v_cvt_f32_i32_e32 v2, s11
	v_rcp_iflag_f32_e32 v4, v3
	s_ashr_i32 s4, s11, 30
	s_or_b32 s4, s4, 1
	v_mov_b32_e32 v147, 0
	v_mul_f32_e32 v4, v2, v4
	v_trunc_f32_e32 v4, v4
	v_fma_f32 v2, -v4, v3, v2
	v_cvt_i32_f32_e32 v4, v4
	v_cmp_ge_f32_e64 s[12:13], |v2|, v3
	s_and_b64 s[12:13], s[12:13], exec
	s_cselect_b32 s4, s4, 0
	v_readfirstlane_b32 s12, v4
	s_add_i32 s4, s12, s4
	s_mul_i32 s12, s4, s15
	s_sub_i32 s11, s11, s12
	s_sext_i32_i8 s11, s11
	s_add_i32 s28, s14, s11
	s_ashr_i32 s29, s28, 31
	s_bfe_i64 s[14:15], s[4:5], 0x80000
	s_lshl_b64 s[12:13], s[28:29], 20
	s_lshl_b64 s[14:15], s[14:15], 20
	s_add_u32 s34, s39, s14
	s_addc_u32 s35, s40, s15
	s_add_i32 s29, s41, 0
	s_add_i32 m0, s29, 0x10000
	v_mov_b32_e32 v149, v147
	global_load_lds_dwordx4 v146, s[34:35]
	s_add_i32 m0, s29, 0x12000
	s_add_u32 s14, s34, 0x80000
	global_load_lds_dwordx4 v148, s[34:35]
	s_addc_u32 s15, s35, 0
	s_add_i32 m0, s29, 0x14000
	s_mov_b32 s11, 0
	global_load_lds_dwordx4 v146, s[14:15]
	s_add_i32 m0, s29, 0x16000
	s_add_u32 s30, s33, s12
	s_addc_u32 s31, s38, s13
	s_add_i32 s44, s29, 0x2000
	global_load_lds_dwordx4 v148, s[14:15]
	s_mov_b32 m0, s29
	s_add_u32 s12, s30, 0x80000
	global_load_lds_dwordx4 v146, s[30:31]
	s_mov_b32 m0, s44
	s_addc_u32 s13, s31, 0
	s_add_i32 s45, s29, 0x4000
	global_load_lds_dwordx4 v148, s[30:31]
	s_mov_b32 m0, s45
	s_add_i32 s46, s29, 0x6000
	global_load_lds_dwordx4 v146, s[12:13]
	s_mov_b32 m0, s46
	s_cmp_eq_u32 s18, 1
	global_load_lds_dwordx4 v148, s[12:13]
	v_lshl_add_u64 v[8:9], s[34:35], 0, v[146:147]
	s_waitcnt lgkmcnt(0)
	v_lshl_add_u64 v[6:7], s[34:35], 0, v[148:149]
	v_lshl_add_u64 v[2:3], s[30:31], 0, v[146:147]
	s_cselect_b64 s[12:13], -1, 0
	s_cmp_lg_u32 s18, 1
	v_lshl_add_u64 v[4:5], s[30:31], 0, v[148:149]
	s_cbranch_scc1 .LBB0_2225
	s_barrier

; #define LAS __attribute__((address_space(3)))
; __device__ __forceinline__ void rem_table(Frame& F, LAS signed char* rem) {
;     for (int i = F.tid; i < (M / 256) * 16; i += 512) rem[i] = -1;
;     __syncthreads();
; __global__ void __launch_bounds__(512, 2) mk_fwd(Args args) {
;     ...
;     if (IN(7)) { p7_x1_rows(F);
.LBB0_2301:
	s_cmp_lt_u32 s98, 4
	s_cbranch_scc0 .Lprio_x3
	s_setprio 1
.Lprio_x3:
	s_cmp_lt_i32 s90, 8
	s_cselect_b64 s[0:1], -1, 0
	s_and_b64 s[18:19], s[0:1], s[2:3]
	s_andn2_b64 vcc, exec, s[18:19]
	s_cbranch_vccnz .LBB0_2454
	s_movk_i32 s0, 0x220
	v_cmp_gt_u32_e32 vcc, s0, v0
	s_and_saveexec_b64 s[2:3], vcc
	s_cbranch_execz .LBB0_2309
	v_sub_u32_e64 v1, 32, v0 clamp
	v_add_u32_e32 v1, 0x1ff, v1
	s_waitcnt vmcnt(0)
	v_lshrrev_b32_e32 v2, 9, v1
	s_mov_b32 s4, 0
	v_mov_b32_e32 v1, v2
	s_mov_b32 s5, 1
	v_add_u32_e32 v3, 0, v0
	s_mov_b64 s[6:7], 0
	v_mov_b32_e32 v4, 0xff
	s_mov_b32 s8, s4
	s_branch .LBB0_2305

; #define LAS __attribute__((address_space(3)))
;     __host__ __device__ void tile_of(int L, Unit& u) const {
;         int wgid = L; { const int q = nwg / NXCD, r = nwg % NXCD, xcd = wgid % NXCD, off = wgid / NXCD; wgid = (xcd < r ? xcd * (q + 1) : r * (q + 1) + (xcd - r) * q) + off; }
;         tile_of_wgid(wgid, u);
;     }
; __global__ void __launch_bounds__(512, 2) mk_fwd(Args args) {
;     ...
;     if (IN(8)) { pg8::Gemm g{WSP(bf16_t, WS_X1B), WSP(bf16_t, WS_BT3Q), M, 2 * DFF, DM / 2, DM / 2, DM / 2}; pg8::StaticOrder S; S.init(M, 2 * DFF, F.G, (int)blockIdx.x);
;         EpiUpConv E{WSP(bf16_t, WS_ACT), WSP(float, WS_RF3), ctl + CW_CMAX3, F.out, F.in[26], F.in[27], F.in[6], (LAS float*)(F.lds + RING_BYTES), WSP(unsigned long long, WS_HALO), ctl + CW_HFLAG, ctl + CW_TMO};
;         pg8::gemm_phase<EpiUpConv, pg8::GeomPlain, pg8::StaticOrder, true, true>(F.lds, g, S, E);
.LBB0_2508:
	s_setprio 0
	s_cmp_lt_i32 s90, 9
	s_cselect_b64 s[2:3], -1, 0
	s_and_b64 s[20:21], s[2:3], s[0:1]
	s_andn2_b64 vcc, exec, s[20:21]
	s_cbranch_vccnz .LBB0_2744
	s_cmpk_lt_i32 s92, 0xcc0
	s_cselect_b64 s[4:5], -1, 0
	s_cmpk_gt_i32 s92, 0xcbf
	v_readfirstlane_b32 s6, v0
	s_cbranch_scc1 .LBB0_2511
	s_ashr_i32 s2, s92, 31
	s_lshr_b32 s2, s2, 29
	s_add_i32 s2, s92, s2
	s_ashr_i32 s3, s2, 3
	s_and_b32 s2, s2, -8
	s_sub_i32 s2, s92, s2
	s_cmp_lt_i32 s2, 0
	s_movk_i32 s7, 0x199
	s_cselect_b32 s7, s7, 0x198
	s_mul_i32 s2, s2, s7
	s_add_i32 s2, s2, s3
	s_mul_hi_i32 s3, s2, 0x2aaaaaab
	s_lshr_b32 s7, s3, 31
	s_ashr_i32 s3, s3, 7
	s_add_i32 s3, s3, s7
	s_lshl_b32 s7, s3, 3
	s_sub_i32 s8, 34, s7
	s_min_u32 s8, s8, 8
	s_mulk_i32 s3, 0x300
	s_sub_i32 s9, s2, s3
	s_waitcnt vmcnt(0)
	v_cvt_f32_ubyte0_e32 v2, s8
	v_cvt_f32_i32_e32 v1, s9
	v_rcp_iflag_f32_e32 v3, v2
	s_ashr_i32 s2, s9, 30
	s_or_b32 s10, s2, 1
	v_mul_f32_e32 v3, v1, v3
	v_trunc_f32_e32 v3, v3
	v_fma_f32 v1, -v3, v2, v1
	v_cvt_i32_f32_e32 v3, v3
	v_cmp_ge_f32_e64 s[2:3], |v1|, v2
	s_and_b64 s[2:3], s[2:3], exec
	s_cselect_b32 s2, s10, 0
	v_readfirstlane_b32 s3, v3
	s_add_i32 s3, s3, s2
	s_sext_i32_i16 s2, s3
	s_mul_i32 s3, s3, s8
	s_sub_i32 s3, s9, s3
	s_sext_i32_i16 s3, s3
	s_add_i32 s64, s7, s3

; __device__ __forceinline__ float bf_lo(unsigned w) { return __uint_as_float(w << 16); }
;     constexpr int RL = 2048 * NC;
;     for (int r = gw; r < R; r += NGW) { const bf16_t* sr = src + (size_t)r * RL; u32x4 pk[NC][4]; float mx = 0.f;
;         float sq = 0.f; if constexpr (RGN) sq = ssq[(size_t)r * 64 + lane];
; #pragma unroll
;         for (int i = 0; i < NC; ++i)
; #pragma unroll
;             for (int q = 0; q < 4; ++q) pk[i][q] = __builtin_nontemporal_load((const u32x4*)(sr + 2048 * i + 8 * (lane + 64 * q)));
; #pragma unroll
;         for (int i = 0; i < NC; ++i) { float x[32];
; #pragma unroll
;             for (int q = 0; q < 4; ++q) { const u32x4 w = pk[i][q]; x[8 * q] = bf_lo(w.x); x[8 * q + 1] = bf_hi(w.x); x[8 * q + 2] = bf_lo(w.y); x[8 * q + 3] = bf_hi(w.y); x[8 * q + 4] = bf_lo(w.z); x[8 * q + 5] = bf_hi(w.z); x[8 * q + 6] = bf_lo(w.w); x[8 * q + 7] = bf_hi(w.w); }
;             fwht32(x);
;             if constexpr (RGN) { if (i == 0) { const float rs = rsqrtf(wave_sum(sq) * (1.0f / DRNN) + EPS);
; #pragma unroll
;                     for (int e = 0; e < 32; ++e) x[e] *= rs; } }
; #pragma unroll
;             for (int q = 0; q < 4; ++q) { pk[i][q].x = cvt_pk_bf16(x[8 * q], x[8 * q + 1]); pk[i][q].y = cvt_pk_bf16(x[8 * q + 2], x[8 * q + 3]); pk[i][q].z = cvt_pk_bf16(x[8 * q + 4], x[8 * q + 5]); pk[i][q].w = cvt_pk_bf16(x[8 * q + 6], x[8 * q + 7]); }
; #pragma unroll
;             for (int e = 0; e < 32; ++e) mx = fmaxf(mx, fabsf(x[e])); }
; #pragma unroll
;         for (int o = 1; o < 64; o <<= 1) mx = fmaxf(mx, __shfl_xor(mx, o));
;         mx = fmaxf(mx * 1.004f, 1e-30f);
;         if (lane == 0) scale[r] = mx * (0.17677669529663687f / 127.0f);
;         const float inv = 127.0f / mx;
; #pragma unroll
;         for (int i = 0; i < NC; ++i) { unsigned char* d = dst + (size_t)r * RL + 2048 * i + 8 * lane;
; #pragma unroll
;             for (int q = 0; q < 4; ++q) { const u32x4 w = pk[i][q]; u32x2 o; o.x = q8_pack4(bf_lo(w.x), bf_hi(w.x), bf_lo(w.y), bf_hi(w.y), inv); o.y = q8_pack4(bf_lo(w.z), bf_hi(w.z), bf_lo(w.w), bf_hi(w.w), inv);
;                 *(u32x2*)(d + 512 * q) = o; } } }
; __global__ void __launch_bounds__(512, 2) mk_fwd(Args args) {
;     ...
;     if (IN(9)) { rotq_rows_i8(WSP(bf16_t, WS_ACT), WSP(unsigned char, WS_ACTQ), WSP(float, WS_SA4), M, F.wave * F.G + (int)blockIdx.x, F.G * 8, F.lane); } SEAM(9);
.LBB0_2798:
	s_cmp_lt_u32 s98, 4
	s_cbranch_scc0 .Lprio_x4
	s_setprio 1
.Lprio_x4:
	s_cmp_lt_i32 s90, 10
	s_cselect_b64 s[0:1], -1, 0
	s_and_b64 s[0:1], s[0:1], s[2:3]
	s_andn2_b64 vcc, exec, s[0:1]
	s_cbranch_vccnz .LBB0_2804
	s_add_i32 s13, s66, s92
	s_cmpk_gt_i32 s13, 0x21ff
	s_cbranch_scc1 .LBB0_2804
	s_lshl_b32 s2, s96, 3
	s_ashr_i32 s3, s92, 31
	s_ashr_i32 s6, s66, 31
	s_add_u32 s10, s92, s66
	s_addc_u32 s11, s3, s6
	s_lshl_b64 s[6:7], s[10:11], 2
	s_add_u32 s16, s6, 0x19153000
	s_addc_u32 s17, s7, 0
	s_ashr_i32 s3, s2, 31
	s_lshl_b64 s[6:7], s[2:3], 2
	s_mul_i32 s3, s11, 0x6000
	s_mul_hi_u32 s8, s10, 0x6000
	s_add_i32 s8, s8, s3
	s_mul_i32 s3, s10, 0x6000
	v_mbcnt_lo_u32_b32 v1, -1, 0
	v_lshl_or_b32 v82, v238, 4, s3
	s_mul_i32 s3, s11, 0x3000
	s_mul_hi_u32 s11, s10, 0x3000
	v_mbcnt_hi_u32_b32 v1, -1, v1
	s_add_i32 s11, s11, s3
	s_mul_i32 s3, s10, 0x3000
	s_waitcnt vmcnt(0)
	v_and_b32_e32 v2, 64, v1
	v_cmp_eq_u32_e64 s[4:5], 0, v238
	v_mov_b32_e32 v83, s8
	s_mul_i32 s8, s96, 0x30000
	s_mul_hi_i32 s9, s2, 0x6000
	v_lshl_or_b32 v84, v238, 3, s3
	v_mov_b32_e32 v85, s11
	s_mul_i32 s10, s96, 0x18000
	s_mul_hi_i32 s11, s2, 0x3000
	v_add_u32_e32 v86, 64, v2
	v_xor_b32_e32 v87, 1, v1
	v_xor_b32_e32 v88, 2, v1
	v_xor_b32_e32 v89, 4, v1
	v_xor_b32_e32 v90, 8, v1
	v_xor_b32_e32 v91, 16, v1
	v_xor_b32_e32 v92, 32, v1
	v_mov_b32_e32 v93, 0
	s_mov_b32 s3, 0x42fe0000
	s_mov_b32 s12, 0x4b400000
	s_mov_b32 s18, 0x5090f000
	s_mov_b32 s19, 0x50910000
	s_mov_b32 s20, 0x50911000
	s_branch .LBB0_2802

;     static __device__ __forceinline__ size_t a_off(const Gemm& g, const Unit& u) { return (size_t)u.pm * 256 * g.lda * 2; }
;     static __device__ __forceinline__ size_t b_off(const Gemm& g, const Unit& u) { return (size_t)u.pn * 256 * g.ldb * 2; }
;     static __device__ __forceinline__ size_t a_off(const Gemm& g, const Unit& u) { return ((size_t)u.pm * 256 * g.lda + (size_t)(u.pn >> 1) * 256) * 2; }
;     static __device__ __forceinline__ size_t b_off(const Gemm& g, const Unit& u) { return (size_t)u.pn * 256 * g.ldb * 2; }
;     __host__ __device__ bool next(int i, Unit& u) const { const long L = (long)i * G + c; if (L >= limit) return false; tile_of((int)L, u); return true; }
; #define PG8_WAIT_V(n) asm volatile("s_waitcnt vmcnt(" #n ")" ::: "memory")
; template <class Epi, class Geom, class Sched, bool ALIGN_EPI, bool I8 = false>
; __device__ __forceinline__ void gemm_phase(LAS unsigned char* lds, const Gemm g, const Sched& S, const Epi& E) {
;     ...
;     Unit cur, nxt; int ui = 0;
;     if (!S.next(0, cur)) return;
;     f32x4 acc[2][2][4][2];
; #pragma unroll
;     for (int a = 0; a < 2; ++a)
; #pragma unroll
;         for (int b = 0; b < 2; ++b)
; #pragma unroll
;             for (int m = 0; m < 4; ++m)
; #pragma unroll
;                 for (int n = 0; n < 2; ++n) acc[a][b][m][n] = (f32x4){0.f, 0.f, 0.f, 0.f};
;     bf16x8 At[4][2], B0[2][2], B1[2][2];
;     const char* cA = (const char*)g.A + Geom::a_off(g, cur); const char* cB = (const char*)g.Bt + Geom::b_off(g, cur);
;     PG8_STAGE(PG8_SB(0, 0), cB, voffB); PG8_STAGE(PG8_SB(0, 1), cB + hsB, voffB); PG8_STAGE(PG8_SA(0, 0), cA, voffA); PG8_STAGE(PG8_SA(0, 1), cA + hsA, voffA);
;     if (wr == 1) PG8_BAR;
;     PG8_WAIT_V(2); PG8_BAR;
;     PG8_STAGE(PG8_SB(1, 0), cB + kstep, voffB); PG8_STAGE(PG8_SA(1, 0), cA + kstep, voffA); PG8_STAGE(PG8_SB(1, 1), cB + hsB + kstep, voffB);
;     PG8_WAIT_V(6); PG8_BAR;
; __global__ void __launch_bounds__(512, 2) mk_fwd(Args args) {
;     ...
;     if (IN(10)) { pg8::Gemm g{WSP(bf16_t, WS_ACTQ), WSP(bf16_t, WS_BT4Q), M, DM, DFF / 2, DFF / 2, DFF / 2}; pg8::StaticOrder S; S.init(M, DM, F.G, (int)blockIdx.x);
;         const bool split = (F.G == 256); if (split) S.limit = REM_FIRST;
;         EpiX2 E{WSP(bf16_t, WS_X1), WSP(bf16_t, WS_X2B), WSP(float, WS_SA4), WSP(float, WS_SW4)};
;         pg8::gemm_phase<EpiX2, pg8::GeomPlain, pg8::StaticOrder, true, true>(F.lds, g, S, E);
.LBB0_2858:
	s_setprio 0
	s_cmp_lt_i32 s90, 11
	s_cselect_b64 s[0:1], -1, 0
	s_and_b64 s[6:7], s[0:1], s[2:3]
	s_andn2_b64 vcc, exec, s[6:7]
	s_cbranch_vccnz .LBB0_2888
	s_add_u32 s42, s86, 0x5090f000
	s_addc_u32 s43, s87, 0
	s_add_u32 s44, s86, 0x56f0f000
	s_addc_u32 s45, s87, 0
	s_cmpk_eq_i32 s96, 0x100
	s_cselect_b64 s[12:13], -1, 0
	s_movk_i32 s2, 0x200
	s_and_b64 s[0:1], s[12:13], exec
	s_cselect_b32 s14, s2, 0x220
	s_add_u32 s8, s86, 0x19153000
	s_addc_u32 s9, s87, 0
	s_waitcnt vmcnt(0)
	v_lshrrev_b32_e32 v2, 3, v0
	s_add_u32 s10, s86, 0x1915b800
	v_and_or_b32 v159, v2, 48, v239
	v_or_b32_e32 v2, 64, v2
	s_movk_i32 s0, 0x70
	s_addc_u32 s11, s87, 0
	v_bitop3_b32 v1, v234, v241, 48 bitop3:0x6c
	v_and_or_b32 v169, v2, s0, v239
	v_and_b32_e32 v2, 0x3c0, v240
	v_and_b32_e32 v3, 32, v233
	v_readfirstlane_b32 s1, v0
	v_or_b32_e32 v165, v1, v236
	s_cmp_ge_i32 s92, s14
	s_waitcnt lgkmcnt(0)
	v_bitop3_b32 v155, v237, v3, v2 bitop3:0x36
	s_cbranch_scc1 .LBB0_2879
	s_ashr_i32 s47, s92, 31
	s_lshr_b32 s0, s47, 29
	s_add_i32 s0, s92, s0
	s_lshr_b32 s5, s1, 6
	s_ashr_i32 s2, s0, 3
	s_and_b32 s0, s0, -8
	s_lshr_b32 s4, s1, 8
	s_lshl_b32 s46, s5, 10
	s_sub_i32 s0, s92, s0
	s_cmp_lt_i32 s0, 0
	s_movk_i32 s48, 0x45
	s_cselect_b32 s3, s48, 0x44
	s_mul_i32 s0, s0, s3
	s_add_i32 s0, s0, s2
	s_ashr_i32 s2, s0, 31
	s_lshr_b32 s2, s2, 25
	s_add_i32 s2, s0, s2
	s_ashr_i32 s3, s2, 7
	s_lshl_b32 s15, s3, 3
	s_sub_i32 s3, 34, s15
	s_min_u32 s16, s3, 8
	s_and_b32 s2, s2, 0xffffff80
	s_sub_i32 s17, s0, s2
	v_cvt_f32_ubyte0_e32 v3, s16
	v_cvt_f32_i32_e32 v2, s17
	v_rcp_iflag_f32_e32 v4, v3
	s_ashr_i32 s0, s17, 30
	s_or_b32 s0, s0, 1
	v_mul_u32_u24_e32 v11, 0x3000, v159
	v_mul_f32_e32 v4, v2, v4
	v_trunc_f32_e32 v4, v4
	v_fma_f32 v2, -v4, v3, v2
	v_cvt_i32_f32_e32 v4, v4
	v_cmp_ge_f32_e64 s[2:3], |v2|, v3
	s_and_b64 s[2:3], s[2:3], exec
	s_cselect_b32 s0, s0, 0
	v_readfirstlane_b32 s2, v4
	s_add_i32 s0, s2, s0
	s_mul_i32 s2, s0, s16
	s_sub_i32 s2, s17, s2
	s_sext_i32_i8 s2, s2
	s_add_i32 s58, s15, s2
	s_bfe_i64 s[2:3], s[0:1], 0x80000
	s_mul_hi_i32 s3, s2, 0x300000
	s_mul_i32 s2, s2, 0x300000
	s_add_u32 s38, s44, s2
	s_addc_u32 s39, s45, s3
	s_add_i32 s33, s46, 0
	v_or_b32_e32 v144, v11, v165
	s_add_i32 m0, s33, 0x10000
	v_mul_u32_u24_e32 v10, 0x3000, v169
	global_load_lds_dwordx4 v144, s[38:39]
	s_add_i32 m0, s33, 0x12000
	v_or_b32_e32 v142, v10, v165
	s_add_u32 s2, s38, 0x180000
	global_load_lds_dwordx4 v142, s[38:39]
	s_addc_u32 s3, s39, 0
	s_add_i32 m0, s33, 0x14000
	s_mul_i32 s16, s58, 0x300000
	global_load_lds_dwordx4 v144, s[2:3]
	s_add_i32 m0, s33, 0x16000
	s_mul_hi_i32 s15, s58, 0x300000
	s_add_u32 s36, s42, s16
	s_addc_u32 s37, s43, s15
	s_add_i32 s49, s33, 0x2000
	global_load_lds_dwordx4 v142, s[2:3]
	s_mov_b32 m0, s33
	s_add_u32 s2, s36, 0x180000
	global_load_lds_dwordx4 v144, s[36:37]
	s_mov_b32 m0, s49
	s_addc_u32 s3, s37, 0
	s_add_i32 s50, s33, 0x4000
	global_load_lds_dwordx4 v142, s[36:37]
	s_mov_b32 m0, s50
	s_add_i32 s51, s33, 0x6000
	global_load_lds_dwordx4 v144, s[2:3]
	s_mov_b32 m0, s51
	v_mov_b32_e32 v145, 0
	global_load_lds_dwordx4 v142, s[2:3]
	v_mov_b32_e32 v143, v145
	s_cmp_eq_u32 s4, 1
	s_mov_b32 s15, 0
	v_lshl_add_u64 v[8:9], s[38:39], 0, v[144:145]
	v_lshl_add_u64 v[6:7], s[38:39], 0, v[142:143]
	v_lshl_add_u64 v[2:3], s[36:37], 0, v[144:145]
	s_cselect_b64 s[2:3], -1, 0
	s_cmp_lg_u32 s4, 1
	v_lshl_add_u64 v[4:5], s[36:37], 0, v[142:143]
	s_cbranch_scc1 .LBB0_2862
	s_barrier

; #define LAS __attribute__((address_space(3)))
; __device__ __forceinline__ void rem_table(Frame& F, LAS signed char* rem) {
;     for (int i = F.tid; i < (M / 256) * 16; i += 512) rem[i] = -1;
;     __syncthreads();
;     if (F.G == 256 && F.tid < REM_N) { pg8::StaticOrder S; S.init(M, DM, F.G, 0); pg8::Unit u; S.tile_of(REM_FIRST + F.tid, u); rem[u.pm * 16 + u.pn] = (signed char)F.tid; }
;     __syncthreads();
; }
; __global__ void __launch_bounds__(512, 2) mk_fwd(Args args) {
;     ...
;     if (IN(11)) { p_final(F); }
.LBB0_2942:
	s_cmp_lt_u32 s98, 4
	s_cbranch_scc0 .Lprio_x5
	s_setprio 1
.Lprio_x5:
	s_cmp_lt_i32 s90, 12
	s_cselect_b64 s[2:3], -1, 0
	s_and_b64 s[0:1], s[2:3], s[0:1]
	s_andn2_b64 vcc, exec, s[0:1]
	s_cbranch_vccnz .LBB0_3086
	s_movk_i32 s0, 0x220
	v_cmp_gt_u32_e32 vcc, s0, v0
	s_and_saveexec_b64 s[2:3], vcc
	s_cbranch_execz .LBB0_2950
	v_sub_u32_e64 v1, 32, v0 clamp
	v_add_u32_e32 v1, 0x1ff, v1
	s_waitcnt vmcnt(0)
	v_lshrrev_b32_e32 v2, 9, v1
	s_mov_b32 s4, 0
	v_mov_b32_e32 v1, v2
	s_mov_b32 s5, 1
	v_add_u32_e32 v3, 0, v0
	s_mov_b64 s[6:7], 0
	v_mov_b32_e32 v4, 0xff
	s_mov_b32 s8, s4
	s_branch .LBB0_2946
